# v43: + hand-written topk per-token loop (2 VALU per compare with rotating SGPR masks, half-wave candidate ranking, LDS pair-ranking, DPP wave-sum)
# speedup vs baseline: 1.1180x; 1.0307x over previous
; __device__ void topk_unit(const Params& p, unsigned char* smem, int unit) {
;     ...
;     const unsigned* row = S + tk * 260;
;     unsigned ka[2], kb[2], mxk[2];
; #pragma unroll
;     for (int hf = 0; hf < 2; ++hf) {
;       ka[hf] = row[hf * 128 + lane];
;       kb[hf] = row[hf * 128 + 64 + lane];
;       mxk[hf] = ka[hf] > kb[hf] ? ka[hf] : kb[hf];
;       Ms[hf * 96 + lane] = mxk[hf];
;     }
;     int cnt[2][4];
; #pragma unroll
;     for (int hf = 0; hf < 2; ++hf)
; #pragma unroll
;       for (int e = 0; e < 4; ++e) cnt[hf][e] = 0;
; #pragma unroll
;     for (int j = 0; j < 16; ++j)
; #pragma unroll
;       for (int hf = 0; hf < 2; ++hf) {
;         u32x4 x = *(const u32x4*)(Ms + hf * 96 + j * 4);
; #pragma unroll
;         for (int e = 0; e < 4; ++e) cnt[hf][e] += (x[e] > mxk[hf]) ? 1 : 0;
;       }
.LBB0_1087:
	s_mov_b64 s[46:47], exec
	v_lshrrev_b32_e32 v89, 5, v138
	v_lshlrev_b32_e32 v94, 6, v89
	v_mul_u32_u24_e32 v89, 0x180, v89
	v_add_u32_e32 v94, v99, v94
	v_add_u32_e32 v79, v101, v89
	v_add_u32_e32 v89, v105, v89
	v_sub_u32_e32 v92, 0xff, v65
	s_mov_b32 s3, 0xffffff00
.Ltk2_loop:
	v_add_u32_e32 v8, s12, v103
	ds_read2st64_b32 v[2:3], v8 offset1:1
	ds_read2st64_b32 v[4:5], v8 offset0:2 offset1:3
	v_mov_b32_e32 v9, 0
	v_mov_b32_e32 v10, 0
	v_mov_b32_e32 v11, 0
	v_mov_b32_e32 v95, 0
	s_waitcnt lgkmcnt(0)
	v_max_u32_e32 v6, v2, v3
	v_max_u32_e32 v7, v4, v5
	ds_write_b32 v104, v6
	ds_write_b32 v104, v7 offset:384
	ds_read_b128 v[12:15], v101
	ds_read_b128 v[16:19], v101 offset:16
	ds_read_b128 v[20:23], v101 offset:32
	ds_read_b128 v[24:27], v101 offset:48
	ds_read_b128 v[28:31], v101 offset:384
	ds_read_b128 v[32:35], v101 offset:400
	ds_read_b128 v[36:39], v101 offset:416
	ds_read_b128 v[40:43], v101 offset:432
	s_waitcnt lgkmcnt(4)
	v_cmp_gt_u32_e64 s[68:69], v12, v6
	v_cmp_gt_u32_e64 s[70:71], v13, v6
	v_cmp_gt_u32_e64 s[72:73], v14, v6
	v_cmp_gt_u32_e64 s[74:75], v15, v6
	v_addc_co_u32_e64 v9, s[76:77], 0, v9, s[68:69]
	v_addc_co_u32_e64 v10, s[76:77], 0, v10, s[70:71]
	v_addc_co_u32_e64 v9, s[76:77], 0, v9, s[72:73]
	v_addc_co_u32_e64 v10, s[76:77], 0, v10, s[74:75]
	v_cmp_gt_u32_e64 s[68:69], v16, v6
	v_cmp_gt_u32_e64 s[70:71], v17, v6
	v_cmp_gt_u32_e64 s[72:73], v18, v6
	v_cmp_gt_u32_e64 s[74:75], v19, v6
	v_addc_co_u32_e64 v9, s[76:77], 0, v9, s[68:69]
	v_addc_co_u32_e64 v10, s[76:77], 0, v10, s[70:71]
	v_addc_co_u32_e64 v9, s[76:77], 0, v9, s[72:73]
	v_addc_co_u32_e64 v10, s[76:77], 0, v10, s[74:75]
	v_cmp_gt_u32_e64 s[68:69], v20, v6
	v_cmp_gt_u32_e64 s[70:71], v21, v6
	v_cmp_gt_u32_e64 s[72:73], v22, v6
	v_cmp_gt_u32_e64 s[74:75], v23, v6
	v_addc_co_u32_e64 v9, s[76:77], 0, v9, s[68:69]
	v_addc_co_u32_e64 v10, s[76:77], 0, v10, s[70:71]
	v_addc_co_u32_e64 v9, s[76:77], 0, v9, s[72:73]
	v_addc_co_u32_e64 v10, s[76:77], 0, v10, s[74:75]
	v_cmp_gt_u32_e64 s[68:69], v24, v6
	v_cmp_gt_u32_e64 s[70:71], v25, v6
	v_cmp_gt_u32_e64 s[72:73], v26, v6
	v_cmp_gt_u32_e64 s[74:75], v27, v6
	v_addc_co_u32_e64 v9, s[76:77], 0, v9, s[68:69]
	v_addc_co_u32_e64 v10, s[76:77], 0, v10, s[70:71]
	v_addc_co_u32_e64 v9, s[76:77], 0, v9, s[72:73]
	v_addc_co_u32_e64 v10, s[76:77], 0, v10, s[74:75]
	ds_read_b128 v[12:15], v101 offset:64
	ds_read_b128 v[16:19], v101 offset:80
	ds_read_b128 v[20:23], v101 offset:96
	ds_read_b128 v[24:27], v101 offset:112
	s_waitcnt lgkmcnt(4)
	v_cmp_gt_u32_e64 s[68:69], v28, v7
	v_cmp_gt_u32_e64 s[70:71], v29, v7
	v_cmp_gt_u32_e64 s[72:73], v30, v7
	v_cmp_gt_u32_e64 s[74:75], v31, v7
	v_addc_co_u32_e64 v11, s[76:77], 0, v11, s[68:69]
	v_addc_co_u32_e64 v95, s[76:77], 0, v95, s[70:71]
	v_addc_co_u32_e64 v11, s[76:77], 0, v11, s[72:73]
	v_addc_co_u32_e64 v95, s[76:77], 0, v95, s[74:75]
	v_cmp_gt_u32_e64 s[68:69], v32, v7
	v_cmp_gt_u32_e64 s[70:71], v33, v7
	v_cmp_gt_u32_e64 s[72:73], v34, v7
	v_cmp_gt_u32_e64 s[74:75], v35, v7
	v_addc_co_u32_e64 v11, s[76:77], 0, v11, s[68:69]
	v_addc_co_u32_e64 v95, s[76:77], 0, v95, s[70:71]
	v_addc_co_u32_e64 v11, s[76:77], 0, v11, s[72:73]
	v_addc_co_u32_e64 v95, s[76:77], 0, v95, s[74:75]
	v_cmp_gt_u32_e64 s[68:69], v36, v7
	v_cmp_gt_u32_e64 s[70:71], v37, v7
	v_cmp_gt_u32_e64 s[72:73], v38, v7
	v_cmp_gt_u32_e64 s[74:75], v39, v7
	v_addc_co_u32_e64 v11, s[76:77], 0, v11, s[68:69]
	v_addc_co_u32_e64 v95, s[76:77], 0, v95, s[70:71]
	v_addc_co_u32_e64 v11, s[76:77], 0, v11, s[72:73]
	v_addc_co_u32_e64 v95, s[76:77], 0, v95, s[74:75]
	v_cmp_gt_u32_e64 s[68:69], v40, v7
	v_cmp_gt_u32_e64 s[70:71], v41, v7
	v_cmp_gt_u32_e64 s[72:73], v42, v7
	v_cmp_gt_u32_e64 s[74:75], v43, v7
	v_addc_co_u32_e64 v11, s[76:77], 0, v11, s[68:69]
	v_addc_co_u32_e64 v95, s[76:77], 0, v95, s[70:71]
	v_addc_co_u32_e64 v11, s[76:77], 0, v11, s[72:73]
	v_addc_co_u32_e64 v95, s[76:77], 0, v95, s[74:75]
	ds_read_b128 v[28:31], v101 offset:448
	ds_read_b128 v[32:35], v101 offset:464
	ds_read_b128 v[36:39], v101 offset:480
	ds_read_b128 v[40:43], v101 offset:496
	s_waitcnt lgkmcnt(4)
	v_cmp_gt_u32_e64 s[68:69], v12, v6
	v_cmp_gt_u32_e64 s[70:71], v13, v6
	v_cmp_gt_u32_e64 s[72:73], v14, v6
	v_cmp_gt_u32_e64 s[74:75], v15, v6
	v_addc_co_u32_e64 v9, s[76:77], 0, v9, s[68:69]
	v_addc_co_u32_e64 v10, s[76:77], 0, v10, s[70:71]
	v_addc_co_u32_e64 v9, s[76:77], 0, v9, s[72:73]
	v_addc_co_u32_e64 v10, s[76:77], 0, v10, s[74:75]
	v_cmp_gt_u32_e64 s[68:69], v16, v6
	v_cmp_gt_u32_e64 s[70:71], v17, v6
	v_cmp_gt_u32_e64 s[72:73], v18, v6
	v_cmp_gt_u32_e64 s[74:75], v19, v6
	v_addc_co_u32_e64 v9, s[76:77], 0, v9, s[68:69]
	v_addc_co_u32_e64 v10, s[76:77], 0, v10, s[70:71]
	v_addc_co_u32_e64 v9, s[76:77], 0, v9, s[72:73]
	v_addc_co_u32_e64 v10, s[76:77], 0, v10, s[74:75]
	v_cmp_gt_u32_e64 s[68:69], v20, v6
	v_cmp_gt_u32_e64 s[70:71], v21, v6
	v_cmp_gt_u32_e64 s[72:73], v22, v6
	v_cmp_gt_u32_e64 s[74:75], v23, v6
	v_addc_co_u32_e64 v9, s[76:77], 0, v9, s[68:69]
	v_addc_co_u32_e64 v10, s[76:77], 0, v10, s[70:71]
	v_addc_co_u32_e64 v9, s[76:77], 0, v9, s[72:73]
	v_addc_co_u32_e64 v10, s[76:77], 0, v10, s[74:75]
	v_cmp_gt_u32_e64 s[68:69], v24, v6
	v_cmp_gt_u32_e64 s[70:71], v25, v6
	v_cmp_gt_u32_e64 s[72:73], v26, v6
	v_cmp_gt_u32_e64 s[74:75], v27, v6
	v_addc_co_u32_e64 v9, s[76:77], 0, v9, s[68:69]
	v_addc_co_u32_e64 v10, s[76:77], 0, v10, s[70:71]
	v_addc_co_u32_e64 v9, s[76:77], 0, v9, s[72:73]
	v_addc_co_u32_e64 v10, s[76:77], 0, v10, s[74:75]
	ds_read_b128 v[12:15], v101 offset:128
	ds_read_b128 v[16:19], v101 offset:144
	ds_read_b128 v[20:23], v101 offset:160
	ds_read_b128 v[24:27], v101 offset:176
	s_waitcnt lgkmcnt(4)
; __device__ void topk_unit(const Params& p, unsigned char* smem, int unit) {
;     ...
;     for (int j = 0; j < 16; ++j)
; #pragma unroll
;       for (int hf = 0; hf < 2; ++hf) {
;         u32x4 x = *(const u32x4*)(Ms + hf * 96 + j * 4);
; #pragma unroll
;         for (int e = 0; e < 4; ++e) cnt[hf][e] += (x[e] > mxk[hf]) ? 1 : 0;
;       }
	v_cmp_gt_u32_e64 s[68:69], v28, v7
	v_cmp_gt_u32_e64 s[70:71], v29, v7
	v_cmp_gt_u32_e64 s[72:73], v30, v7
	v_cmp_gt_u32_e64 s[74:75], v31, v7
	v_addc_co_u32_e64 v11, s[76:77], 0, v11, s[68:69]
	v_addc_co_u32_e64 v95, s[76:77], 0, v95, s[70:71]
	v_addc_co_u32_e64 v11, s[76:77], 0, v11, s[72:73]
	v_addc_co_u32_e64 v95, s[76:77], 0, v95, s[74:75]
	v_cmp_gt_u32_e64 s[68:69], v32, v7
	v_cmp_gt_u32_e64 s[70:71], v33, v7
	v_cmp_gt_u32_e64 s[72:73], v34, v7
	v_cmp_gt_u32_e64 s[74:75], v35, v7
	v_addc_co_u32_e64 v11, s[76:77], 0, v11, s[68:69]
	v_addc_co_u32_e64 v95, s[76:77], 0, v95, s[70:71]
	v_addc_co_u32_e64 v11, s[76:77], 0, v11, s[72:73]
	v_addc_co_u32_e64 v95, s[76:77], 0, v95, s[74:75]
	v_cmp_gt_u32_e64 s[68:69], v36, v7
	v_cmp_gt_u32_e64 s[70:71], v37, v7
	v_cmp_gt_u32_e64 s[72:73], v38, v7
	v_cmp_gt_u32_e64 s[74:75], v39, v7
	v_addc_co_u32_e64 v11, s[76:77], 0, v11, s[68:69]
	v_addc_co_u32_e64 v95, s[76:77], 0, v95, s[70:71]
	v_addc_co_u32_e64 v11, s[76:77], 0, v11, s[72:73]
	v_addc_co_u32_e64 v95, s[76:77], 0, v95, s[74:75]
	v_cmp_gt_u32_e64 s[68:69], v40, v7
	v_cmp_gt_u32_e64 s[70:71], v41, v7
	v_cmp_gt_u32_e64 s[72:73], v42, v7
	v_cmp_gt_u32_e64 s[74:75], v43, v7
	v_addc_co_u32_e64 v11, s[76:77], 0, v11, s[68:69]
	v_addc_co_u32_e64 v95, s[76:77], 0, v95, s[70:71]
	v_addc_co_u32_e64 v11, s[76:77], 0, v11, s[72:73]
	v_addc_co_u32_e64 v95, s[76:77], 0, v95, s[74:75]
	ds_read_b128 v[28:31], v101 offset:512
	ds_read_b128 v[32:35], v101 offset:528
	ds_read_b128 v[36:39], v101 offset:544
	ds_read_b128 v[40:43], v101 offset:560
	s_waitcnt lgkmcnt(4)
	v_cmp_gt_u32_e64 s[68:69], v12, v6
	v_cmp_gt_u32_e64 s[70:71], v13, v6
	v_cmp_gt_u32_e64 s[72:73], v14, v6
	v_cmp_gt_u32_e64 s[74:75], v15, v6
	v_addc_co_u32_e64 v9, s[76:77], 0, v9, s[68:69]
	v_addc_co_u32_e64 v10, s[76:77], 0, v10, s[70:71]
	v_addc_co_u32_e64 v9, s[76:77], 0, v9, s[72:73]
	v_addc_co_u32_e64 v10, s[76:77], 0, v10, s[74:75]
	v_cmp_gt_u32_e64 s[68:69], v16, v6
	v_cmp_gt_u32_e64 s[70:71], v17, v6
	v_cmp_gt_u32_e64 s[72:73], v18, v6
	v_cmp_gt_u32_e64 s[74:75], v19, v6
	v_addc_co_u32_e64 v9, s[76:77], 0, v9, s[68:69]
	v_addc_co_u32_e64 v10, s[76:77], 0, v10, s[70:71]
	v_addc_co_u32_e64 v9, s[76:77], 0, v9, s[72:73]
	v_addc_co_u32_e64 v10, s[76:77], 0, v10, s[74:75]
	v_cmp_gt_u32_e64 s[68:69], v20, v6
	v_cmp_gt_u32_e64 s[70:71], v21, v6
	v_cmp_gt_u32_e64 s[72:73], v22, v6
	v_cmp_gt_u32_e64 s[74:75], v23, v6
	v_addc_co_u32_e64 v9, s[76:77], 0, v9, s[68:69]
	v_addc_co_u32_e64 v10, s[76:77], 0, v10, s[70:71]
	v_addc_co_u32_e64 v9, s[76:77], 0, v9, s[72:73]
	v_addc_co_u32_e64 v10, s[76:77], 0, v10, s[74:75]
	v_cmp_gt_u32_e64 s[68:69], v24, v6
	v_cmp_gt_u32_e64 s[70:71], v25, v6
	v_cmp_gt_u32_e64 s[72:73], v26, v6
	v_cmp_gt_u32_e64 s[74:75], v27, v6
	v_addc_co_u32_e64 v9, s[76:77], 0, v9, s[68:69]
	v_addc_co_u32_e64 v10, s[76:77], 0, v10, s[70:71]
	v_addc_co_u32_e64 v9, s[76:77], 0, v9, s[72:73]
	v_addc_co_u32_e64 v10, s[76:77], 0, v10, s[74:75]
	ds_read_b128 v[12:15], v101 offset:192
	ds_read_b128 v[16:19], v101 offset:208
	ds_read_b128 v[20:23], v101 offset:224
	ds_read_b128 v[24:27], v101 offset:240
	s_waitcnt lgkmcnt(4)
	v_cmp_gt_u32_e64 s[68:69], v28, v7
	v_cmp_gt_u32_e64 s[70:71], v29, v7
	v_cmp_gt_u32_e64 s[72:73], v30, v7
	v_cmp_gt_u32_e64 s[74:75], v31, v7
	v_addc_co_u32_e64 v11, s[76:77], 0, v11, s[68:69]
	v_addc_co_u32_e64 v95, s[76:77], 0, v95, s[70:71]
	v_addc_co_u32_e64 v11, s[76:77], 0, v11, s[72:73]
	v_addc_co_u32_e64 v95, s[76:77], 0, v95, s[74:75]
	v_cmp_gt_u32_e64 s[68:69], v32, v7
	v_cmp_gt_u32_e64 s[70:71], v33, v7
	v_cmp_gt_u32_e64 s[72:73], v34, v7
	v_cmp_gt_u32_e64 s[74:75], v35, v7
	v_addc_co_u32_e64 v11, s[76:77], 0, v11, s[68:69]
	v_addc_co_u32_e64 v95, s[76:77], 0, v95, s[70:71]
	v_addc_co_u32_e64 v11, s[76:77], 0, v11, s[72:73]
	v_addc_co_u32_e64 v95, s[76:77], 0, v95, s[74:75]
	v_cmp_gt_u32_e64 s[68:69], v36, v7
	v_cmp_gt_u32_e64 s[70:71], v37, v7
	v_cmp_gt_u32_e64 s[72:73], v38, v7
	v_cmp_gt_u32_e64 s[74:75], v39, v7
	v_addc_co_u32_e64 v11, s[76:77], 0, v11, s[68:69]
	v_addc_co_u32_e64 v95, s[76:77], 0, v95, s[70:71]
	v_addc_co_u32_e64 v11, s[76:77], 0, v11, s[72:73]
	v_addc_co_u32_e64 v95, s[76:77], 0, v95, s[74:75]
	v_cmp_gt_u32_e64 s[68:69], v40, v7
	v_cmp_gt_u32_e64 s[70:71], v41, v7
	v_cmp_gt_u32_e64 s[72:73], v42, v7
	v_cmp_gt_u32_e64 s[74:75], v43, v7
	v_addc_co_u32_e64 v11, s[76:77], 0, v11, s[68:69]
	v_addc_co_u32_e64 v95, s[76:77], 0, v95, s[70:71]
	v_addc_co_u32_e64 v11, s[76:77], 0, v11, s[72:73]
	v_addc_co_u32_e64 v95, s[76:77], 0, v95, s[74:75]
	ds_read_b128 v[28:31], v101 offset:576
	ds_read_b128 v[32:35], v101 offset:592
	ds_read_b128 v[36:39], v101 offset:608
	ds_read_b128 v[40:43], v101 offset:624
	s_waitcnt lgkmcnt(4)
	v_cmp_gt_u32_e64 s[68:69], v12, v6
	v_cmp_gt_u32_e64 s[70:71], v13, v6
	v_cmp_gt_u32_e64 s[72:73], v14, v6
	v_cmp_gt_u32_e64 s[74:75], v15, v6
	v_addc_co_u32_e64 v9, s[76:77], 0, v9, s[68:69]
	v_addc_co_u32_e64 v10, s[76:77], 0, v10, s[70:71]
	v_addc_co_u32_e64 v9, s[76:77], 0, v9, s[72:73]
	v_addc_co_u32_e64 v10, s[76:77], 0, v10, s[74:75]
	v_cmp_gt_u32_e64 s[68:69], v16, v6
	v_cmp_gt_u32_e64 s[70:71], v17, v6
	v_cmp_gt_u32_e64 s[72:73], v18, v6
	v_cmp_gt_u32_e64 s[74:75], v19, v6
	v_addc_co_u32_e64 v9, s[76:77], 0, v9, s[68:69]
	v_addc_co_u32_e64 v10, s[76:77], 0, v10, s[70:71]
	v_addc_co_u32_e64 v9, s[76:77], 0, v9, s[72:73]
	v_addc_co_u32_e64 v10, s[76:77], 0, v10, s[74:75]
	v_cmp_gt_u32_e64 s[68:69], v20, v6
	v_cmp_gt_u32_e64 s[70:71], v21, v6
	v_cmp_gt_u32_e64 s[72:73], v22, v6
	v_cmp_gt_u32_e64 s[74:75], v23, v6
	v_addc_co_u32_e64 v9, s[76:77], 0, v9, s[68:69]
	v_addc_co_u32_e64 v10, s[76:77], 0, v10, s[70:71]
	v_addc_co_u32_e64 v9, s[76:77], 0, v9, s[72:73]
	v_addc_co_u32_e64 v10, s[76:77], 0, v10, s[74:75]
	v_cmp_gt_u32_e64 s[68:69], v24, v6
	v_cmp_gt_u32_e64 s[70:71], v25, v6
	v_cmp_gt_u32_e64 s[72:73], v26, v6
	v_cmp_gt_u32_e64 s[74:75], v27, v6
	v_addc_co_u32_e64 v9, s[76:77], 0, v9, s[68:69]
	v_addc_co_u32_e64 v10, s[76:77], 0, v10, s[70:71]
	v_addc_co_u32_e64 v9, s[76:77], 0, v9, s[72:73]
	v_addc_co_u32_e64 v10, s[76:77], 0, v10, s[74:75]
	s_waitcnt lgkmcnt(0)
; __device__ void topk_unit(const Params& p, unsigned char* smem, int unit) {
;     ...
;     bool ca_[2], cb_[2];
;     int pa[2], pb[2], ncand[2];
;     const unsigned long long lt = (1ull << lane) - 1ull;
; #pragma unroll
;     for (int hf = 0; hf < 2; ++hf) {
;       const int c_ = cnt[hf][0] + cnt[hf][1] + cnt[hf][2] + cnt[hf][3];
;       const unsigned long long bm = __ballot(c_ == 15);
;       const int srcT = __ffsll((long long)bm) - 1;
;       const unsigned T0 = (unsigned)__shfl((int)mxk[hf], srcT);
;       ca_[hf] = ka[hf] >= T0;
;       cb_[hf] = kb[hf] >= T0;
;       const unsigned long long ba = __ballot(ca_[hf]), bb = __ballot(cb_[hf]);
;       const int na = __popcll(ba);
;       pa[hf] = __popcll(ba & lt);
;       pb[hf] = na + __popcll(bb & lt);
;       ncand[hf] = na + __popcll(bb);
;     }
; #pragma unroll
;     for (int hf = 0; hf < 2; ++hf) {
;       unsigned* Cs = Ms + hf * 96 + 64;
;       if (lane < 32) Cs[lane] = 0u;
;       if (ca_[hf]) Cs[pa[hf]] = ka[hf];
;       if (cb_[hf]) Cs[pb[hf]] = kb[hf];
;     }
;     unsigned my[2];
;     int rk2[2][4];
; #pragma unroll
;     for (int hf = 0; hf < 2; ++hf) {
;       my[hf] = Ms[hf * 96 + 64 + (lane & 31)];
; #pragma unroll
;       for (int e = 0; e < 4; ++e) rk2[hf][e] = 0;
;     }
; #pragma unroll
;     for (int j = 0; j < 8; ++j)
; #pragma unroll
;       for (int hf = 0; hf < 2; ++hf) {
;         u32x4 x = *(const u32x4*)(Ms + hf * 96 + 64 + j * 4);
; #pragma unroll
;         for (int e = 0; e < 4; ++e) rk2[hf][e] += (x[e] > my[hf]) ? 1 : 0;
;       }
; #pragma unroll
;     for (int hf = 0; hf < 2; ++hf) {
;       const int r_ = rk2[hf][0] + rk2[hf][1] + rk2[hf][2] + rk2[hf][3];
;       if (lane < ncand[hf] && r_ < 16) {
;         tops[hf * 16 + r_] = ord_dec(my[hf] & ~127u);
;         topi[hf * 16 + r_] = 127 - (int)(my[hf] & 127u);
;       }
;     }
	v_cmp_gt_u32_e64 s[68:69], v28, v7
	v_cmp_gt_u32_e64 s[70:71], v29, v7
	v_cmp_gt_u32_e64 s[72:73], v30, v7
	v_cmp_gt_u32_e64 s[74:75], v31, v7
	v_addc_co_u32_e64 v11, s[76:77], 0, v11, s[68:69]
	v_addc_co_u32_e64 v95, s[76:77], 0, v95, s[70:71]
	v_addc_co_u32_e64 v11, s[76:77], 0, v11, s[72:73]
	v_addc_co_u32_e64 v95, s[76:77], 0, v95, s[74:75]
	v_cmp_gt_u32_e64 s[68:69], v32, v7
	v_cmp_gt_u32_e64 s[70:71], v33, v7
	v_cmp_gt_u32_e64 s[72:73], v34, v7
	v_cmp_gt_u32_e64 s[74:75], v35, v7
	v_addc_co_u32_e64 v11, s[76:77], 0, v11, s[68:69]
	v_addc_co_u32_e64 v95, s[76:77], 0, v95, s[70:71]
	v_addc_co_u32_e64 v11, s[76:77], 0, v11, s[72:73]
	v_addc_co_u32_e64 v95, s[76:77], 0, v95, s[74:75]
	v_cmp_gt_u32_e64 s[68:69], v36, v7
	v_cmp_gt_u32_e64 s[70:71], v37, v7
	v_cmp_gt_u32_e64 s[72:73], v38, v7
	v_cmp_gt_u32_e64 s[74:75], v39, v7
	v_addc_co_u32_e64 v11, s[76:77], 0, v11, s[68:69]
	v_addc_co_u32_e64 v95, s[76:77], 0, v95, s[70:71]
	v_addc_co_u32_e64 v11, s[76:77], 0, v11, s[72:73]
	v_addc_co_u32_e64 v95, s[76:77], 0, v95, s[74:75]
	v_cmp_gt_u32_e64 s[68:69], v40, v7
	v_cmp_gt_u32_e64 s[70:71], v41, v7
	v_cmp_gt_u32_e64 s[72:73], v42, v7
	v_cmp_gt_u32_e64 s[74:75], v43, v7
	v_addc_co_u32_e64 v11, s[76:77], 0, v11, s[68:69]
	v_addc_co_u32_e64 v95, s[76:77], 0, v95, s[70:71]
	v_addc_co_u32_e64 v11, s[76:77], 0, v11, s[72:73]
	v_addc_co_u32_e64 v95, s[76:77], 0, v95, s[74:75]
	v_add_u32_e32 v9, v9, v10
	v_add_u32_e32 v11, v11, v95
	v_cmp_eq_u32_e64 s[78:79], 15, v9
	v_cmp_eq_u32_e64 s[80:81], 15, v11
	s_nop 1
	s_ff1_i32_b64 s82, s[78:79]
	s_ff1_i32_b64 s83, s[80:81]
	s_nop 1
	v_readlane_b32 s84, v6, s82
	v_readlane_b32 s85, v7, s83
	s_nop 3
	v_cmp_ge_u32_e64 s[86:87], v2, s84
	v_cmp_ge_u32_e64 s[88:89], v3, s84
	v_cmp_ge_u32_e64 s[68:69], v4, s85
	v_cmp_ge_u32_e64 s[70:71], v5, s85
	s_nop 1
	s_bcnt1_i32_b64 s72, s[86:87]
	s_bcnt1_i32_b64 s73, s[68:69]
	v_mbcnt_lo_u32_b32 v44, s86, 0
	v_mbcnt_lo_u32_b32 v45, s88, 0
	v_mbcnt_lo_u32_b32 v46, s68, 0
	v_mbcnt_lo_u32_b32 v47, s70, 0
	v_mbcnt_hi_u32_b32 v44, s87, v44
	v_mbcnt_hi_u32_b32 v45, s89, v45
	v_mbcnt_hi_u32_b32 v46, s69, v46
	v_mbcnt_hi_u32_b32 v47, s71, v47
	v_add_u32_e32 v45, s72, v45
	v_add_u32_e32 v47, s73, v47
	v_lshl_add_u32 v44, v44, 2, v101
	v_lshl_add_u32 v45, v45, 2, v101
	v_lshl_add_u32 v46, v46, 2, v101
	v_lshl_add_u32 v47, v47, 2, v101
	s_mov_b64 exec, s[14:15]
	ds_write_b32 v105, v63 offset:256
	ds_write_b32 v105, v63 offset:640
	s_mov_b64 exec, s[86:87]
	ds_write_b32 v44, v2 offset:256
	s_mov_b64 exec, s[88:89]
	ds_write_b32 v45, v3 offset:256
	s_mov_b64 exec, s[68:69]
	ds_write_b32 v46, v4 offset:640
	s_mov_b64 exec, s[70:71]
	ds_write_b32 v47, v5 offset:640
	s_mov_b64 exec, s[46:47]
	ds_read_b32 v48, v89 offset:256
	ds_read_b128 v[12:15], v79 offset:256
	ds_read_b128 v[16:19], v79 offset:272
	ds_read_b128 v[20:23], v79 offset:288
	ds_read_b128 v[24:27], v79 offset:304
	ds_read_b128 v[28:31], v79 offset:320
	ds_read_b128 v[32:35], v79 offset:336
	ds_read_b128 v[36:39], v79 offset:352
	ds_read_b128 v[40:43], v79 offset:368
	v_mov_b32_e32 v49, 0
	v_mov_b32_e32 v50, 0
	s_waitcnt lgkmcnt(0)
	v_cmp_gt_u32_e64 s[68:69], v12, v48
	v_cmp_gt_u32_e64 s[70:71], v13, v48
	v_cmp_gt_u32_e64 s[72:73], v14, v48
	v_cmp_gt_u32_e64 s[74:75], v15, v48
	v_addc_co_u32_e64 v49, s[76:77], 0, v49, s[68:69]
	v_addc_co_u32_e64 v50, s[76:77], 0, v50, s[70:71]
	v_addc_co_u32_e64 v49, s[76:77], 0, v49, s[72:73]
	v_addc_co_u32_e64 v50, s[76:77], 0, v50, s[74:75]
	v_cmp_gt_u32_e64 s[68:69], v16, v48
	v_cmp_gt_u32_e64 s[70:71], v17, v48
	v_cmp_gt_u32_e64 s[72:73], v18, v48
	v_cmp_gt_u32_e64 s[74:75], v19, v48
	v_addc_co_u32_e64 v49, s[76:77], 0, v49, s[68:69]
	v_addc_co_u32_e64 v50, s[76:77], 0, v50, s[70:71]
	v_addc_co_u32_e64 v49, s[76:77], 0, v49, s[72:73]
	v_addc_co_u32_e64 v50, s[76:77], 0, v50, s[74:75]
	v_cmp_gt_u32_e64 s[68:69], v20, v48
	v_cmp_gt_u32_e64 s[70:71], v21, v48
	v_cmp_gt_u32_e64 s[72:73], v22, v48
	v_cmp_gt_u32_e64 s[74:75], v23, v48
	v_addc_co_u32_e64 v49, s[76:77], 0, v49, s[68:69]
	v_addc_co_u32_e64 v50, s[76:77], 0, v50, s[70:71]
	v_addc_co_u32_e64 v49, s[76:77], 0, v49, s[72:73]
	v_addc_co_u32_e64 v50, s[76:77], 0, v50, s[74:75]
	v_cmp_gt_u32_e64 s[68:69], v24, v48
	v_cmp_gt_u32_e64 s[70:71], v25, v48
	v_cmp_gt_u32_e64 s[72:73], v26, v48
	v_cmp_gt_u32_e64 s[74:75], v27, v48
	v_addc_co_u32_e64 v49, s[76:77], 0, v49, s[68:69]
	v_addc_co_u32_e64 v50, s[76:77], 0, v50, s[70:71]
	v_addc_co_u32_e64 v49, s[76:77], 0, v49, s[72:73]
	v_addc_co_u32_e64 v50, s[76:77], 0, v50, s[74:75]
	v_cmp_gt_u32_e64 s[68:69], v28, v48
	v_cmp_gt_u32_e64 s[70:71], v29, v48
	v_cmp_gt_u32_e64 s[72:73], v30, v48
	v_cmp_gt_u32_e64 s[74:75], v31, v48
	v_addc_co_u32_e64 v49, s[76:77], 0, v49, s[68:69]
	v_addc_co_u32_e64 v50, s[76:77], 0, v50, s[70:71]
	v_addc_co_u32_e64 v49, s[76:77], 0, v49, s[72:73]
	v_addc_co_u32_e64 v50, s[76:77], 0, v50, s[74:75]
	v_cmp_gt_u32_e64 s[68:69], v32, v48
	v_cmp_gt_u32_e64 s[70:71], v33, v48
	v_cmp_gt_u32_e64 s[72:73], v34, v48
	v_cmp_gt_u32_e64 s[74:75], v35, v48
	v_addc_co_u32_e64 v49, s[76:77], 0, v49, s[68:69]
	v_addc_co_u32_e64 v50, s[76:77], 0, v50, s[70:71]
	v_addc_co_u32_e64 v49, s[76:77], 0, v49, s[72:73]
	v_addc_co_u32_e64 v50, s[76:77], 0, v50, s[74:75]
	v_cmp_gt_u32_e64 s[68:69], v36, v48
	v_cmp_gt_u32_e64 s[70:71], v37, v48
	v_cmp_gt_u32_e64 s[72:73], v38, v48
	v_cmp_gt_u32_e64 s[74:75], v39, v48
	v_addc_co_u32_e64 v49, s[76:77], 0, v49, s[68:69]
	v_addc_co_u32_e64 v50, s[76:77], 0, v50, s[70:71]
	v_addc_co_u32_e64 v49, s[76:77], 0, v49, s[72:73]
	v_addc_co_u32_e64 v50, s[76:77], 0, v50, s[74:75]
	v_cmp_gt_u32_e64 s[68:69], v40, v48
	v_cmp_gt_u32_e64 s[70:71], v41, v48
	v_cmp_gt_u32_e64 s[72:73], v42, v48
	v_cmp_gt_u32_e64 s[74:75], v43, v48
	v_addc_co_u32_e64 v49, s[76:77], 0, v49, s[68:69]
	v_addc_co_u32_e64 v50, s[76:77], 0, v50, s[70:71]
	v_addc_co_u32_e64 v49, s[76:77], 0, v49, s[72:73]
	v_addc_co_u32_e64 v50, s[76:77], 0, v50, s[74:75]
	v_add_u32_e32 v49, v49, v50
	v_and_b32_e32 v51, 0xffffff80, v48
	v_cmp_gt_u32_e64 s[74:75], 16, v49
	v_ashrrev_i32_e32 v52, 31, v51
	v_and_b32_e32 v53, 0x7f, v48
	v_not_b32_e32 v52, v52
	v_sub_u32_e32 v53, 0x7f, v53
	v_or_b32_e32 v52, 0x80000000, v52
	v_lshl_add_u32 v54, v49, 2, v94
	v_xor_b32_e32 v51, v51, v52
	s_mov_b64 exec, s[74:75]
	ds_write_b32 v54, v51
	ds_write_b32 v54, v53 offset:128
	s_mov_b64 exec, s[46:47]
	ds_read_b32 v121, v113
	ds_read_b32 v122, v112 offset:64
	ds_read2_b32 v[124:125], v99 offset1:16
	ds_read_b32 v126, v113 offset:128
	ds_read_b32 v127, v112 offset:192
	s_waitcnt lgkmcnt(3)
; __device__ void topk_unit(const Params& p, unsigned char* smem, int unit) {
;     ...
;     float cs = 0.f;
;     unsigned ck = 0u;
;     if (lane < 50) {
;       cs = tops[ca] + tops[16 + cbb];
;       ck = (ord_key(cs) & ~255u) | (unsigned)(255 - (ca * 16 + cbb));
;     }
;     int rkA = 0, rkB = 0;
; #pragma unroll
;     for (int j = 0; j < 50; j += 2) {
;       const unsigned oj = (unsigned)__builtin_amdgcn_readlane((int)ck, j);
;       const unsigned oj2 = (unsigned)__builtin_amdgcn_readlane((int)ck, j + 1);
;       rkA += (oj > ck) ? 1 : 0;
;       rkB += (oj2 > ck) ? 1 : 0;
;     }
;     const int rk = rkA + rkB;
;     const float mx = tops[0] + tops[16];
;     const bool sel = (lane < 50) && (rk < 16);
;     const float ev = sel ? __expf(cs - mx) : 0.f;
;     const float sum = wave_sum(ev);
;     if (sel) {
;       const size_t o = (size_t)(tok0 + tk) * 128 + h * 16 + rk;
;       idxo[o] = topi[ca] * 128 + topi[16 + cbb];
;       go[o] = ev * __builtin_amdgcn_rcpf(sum);
;     }
	v_add_f32_e32 v128, v121, v122
	v_mov_b32_e32 v130, 0
	v_ashrrev_i32_e32 v129, 31, v128
	v_mov_b32_e32 v131, 0
	v_or_b32_e32 v129, 0x80000000, v129
	v_xor_b32_e32 v129, v128, v129
	v_and_or_b32 v129, v129, s3, v92
	v_cndmask_b32_e64 v129, 0, v129, s[4:5]
	ds_write_b32 v104, v129
	ds_read_b128 v[12:15], v101
	ds_read_b128 v[16:19], v101 offset:16
	ds_read_b128 v[20:23], v101 offset:32
	ds_read_b128 v[24:27], v101 offset:48
	ds_read_b128 v[28:31], v101 offset:64
	ds_read_b128 v[32:35], v101 offset:80
	ds_read_b128 v[36:39], v101 offset:96
	ds_read_b128 v[40:43], v101 offset:112
	s_waitcnt lgkmcnt(4)
	v_cmp_gt_u32_e64 s[68:69], v12, v129
	v_cmp_gt_u32_e64 s[70:71], v13, v129
	v_cmp_gt_u32_e64 s[72:73], v14, v129
	v_cmp_gt_u32_e64 s[74:75], v15, v129
	v_addc_co_u32_e64 v130, s[76:77], 0, v130, s[68:69]
	v_addc_co_u32_e64 v131, s[76:77], 0, v131, s[70:71]
	v_addc_co_u32_e64 v130, s[76:77], 0, v130, s[72:73]
	v_addc_co_u32_e64 v131, s[76:77], 0, v131, s[74:75]
	v_cmp_gt_u32_e64 s[68:69], v16, v129
	v_cmp_gt_u32_e64 s[70:71], v17, v129
	v_cmp_gt_u32_e64 s[72:73], v18, v129
	v_cmp_gt_u32_e64 s[74:75], v19, v129
	v_addc_co_u32_e64 v130, s[76:77], 0, v130, s[68:69]
	v_addc_co_u32_e64 v131, s[76:77], 0, v131, s[70:71]
	v_addc_co_u32_e64 v130, s[76:77], 0, v130, s[72:73]
	v_addc_co_u32_e64 v131, s[76:77], 0, v131, s[74:75]
	v_cmp_gt_u32_e64 s[68:69], v20, v129
	v_cmp_gt_u32_e64 s[70:71], v21, v129
	v_cmp_gt_u32_e64 s[72:73], v22, v129
	v_cmp_gt_u32_e64 s[74:75], v23, v129
	v_addc_co_u32_e64 v130, s[76:77], 0, v130, s[68:69]
	v_addc_co_u32_e64 v131, s[76:77], 0, v131, s[70:71]
	v_addc_co_u32_e64 v130, s[76:77], 0, v130, s[72:73]
	v_addc_co_u32_e64 v131, s[76:77], 0, v131, s[74:75]
	v_cmp_gt_u32_e64 s[68:69], v24, v129
	v_cmp_gt_u32_e64 s[70:71], v25, v129
	v_cmp_gt_u32_e64 s[72:73], v26, v129
	v_cmp_gt_u32_e64 s[74:75], v27, v129
	v_addc_co_u32_e64 v130, s[76:77], 0, v130, s[68:69]
	v_addc_co_u32_e64 v131, s[76:77], 0, v131, s[70:71]
	v_addc_co_u32_e64 v130, s[76:77], 0, v130, s[72:73]
	v_addc_co_u32_e64 v131, s[76:77], 0, v131, s[74:75]
	ds_read_b128 v[12:15], v101 offset:128
	ds_read_b128 v[16:19], v101 offset:144
	ds_read_b128 v[20:23], v101 offset:160
	ds_read_b128 v[24:27], v101 offset:176
	ds_read_b128 v[148:151], v101 offset:192
	s_waitcnt lgkmcnt(5)
	v_cmp_gt_u32_e64 s[68:69], v28, v129
	v_cmp_gt_u32_e64 s[70:71], v29, v129
	v_cmp_gt_u32_e64 s[72:73], v30, v129
	v_cmp_gt_u32_e64 s[74:75], v31, v129
	v_addc_co_u32_e64 v130, s[76:77], 0, v130, s[68:69]
	v_addc_co_u32_e64 v131, s[76:77], 0, v131, s[70:71]
	v_addc_co_u32_e64 v130, s[76:77], 0, v130, s[72:73]
	v_addc_co_u32_e64 v131, s[76:77], 0, v131, s[74:75]
	v_cmp_gt_u32_e64 s[68:69], v32, v129
	v_cmp_gt_u32_e64 s[70:71], v33, v129
	v_cmp_gt_u32_e64 s[72:73], v34, v129
	v_cmp_gt_u32_e64 s[74:75], v35, v129
	v_addc_co_u32_e64 v130, s[76:77], 0, v130, s[68:69]
	v_addc_co_u32_e64 v131, s[76:77], 0, v131, s[70:71]
	v_addc_co_u32_e64 v130, s[76:77], 0, v130, s[72:73]
	v_addc_co_u32_e64 v131, s[76:77], 0, v131, s[74:75]
	v_cmp_gt_u32_e64 s[68:69], v36, v129
	v_cmp_gt_u32_e64 s[70:71], v37, v129
	v_cmp_gt_u32_e64 s[72:73], v38, v129
	v_cmp_gt_u32_e64 s[74:75], v39, v129
	v_addc_co_u32_e64 v130, s[76:77], 0, v130, s[68:69]
	v_addc_co_u32_e64 v131, s[76:77], 0, v131, s[70:71]
	v_addc_co_u32_e64 v130, s[76:77], 0, v130, s[72:73]
	v_addc_co_u32_e64 v131, s[76:77], 0, v131, s[74:75]
	v_cmp_gt_u32_e64 s[68:69], v40, v129
	v_cmp_gt_u32_e64 s[70:71], v41, v129
	v_cmp_gt_u32_e64 s[72:73], v42, v129
	v_cmp_gt_u32_e64 s[74:75], v43, v129
	v_addc_co_u32_e64 v130, s[76:77], 0, v130, s[68:69]
	v_addc_co_u32_e64 v131, s[76:77], 0, v131, s[70:71]
	v_addc_co_u32_e64 v130, s[76:77], 0, v130, s[72:73]
	v_addc_co_u32_e64 v131, s[76:77], 0, v131, s[74:75]
	s_waitcnt lgkmcnt(0)
	v_cmp_gt_u32_e64 s[68:69], v12, v129
	v_cmp_gt_u32_e64 s[70:71], v13, v129
	v_cmp_gt_u32_e64 s[72:73], v14, v129
	v_cmp_gt_u32_e64 s[74:75], v15, v129
	v_addc_co_u32_e64 v130, s[76:77], 0, v130, s[68:69]
	v_addc_co_u32_e64 v131, s[76:77], 0, v131, s[70:71]
	v_addc_co_u32_e64 v130, s[76:77], 0, v130, s[72:73]
	v_addc_co_u32_e64 v131, s[76:77], 0, v131, s[74:75]
	v_cmp_gt_u32_e64 s[68:69], v16, v129
	v_cmp_gt_u32_e64 s[70:71], v17, v129
	v_cmp_gt_u32_e64 s[72:73], v18, v129
	v_cmp_gt_u32_e64 s[74:75], v19, v129
	v_addc_co_u32_e64 v130, s[76:77], 0, v130, s[68:69]
	v_addc_co_u32_e64 v131, s[76:77], 0, v131, s[70:71]
	v_addc_co_u32_e64 v130, s[76:77], 0, v130, s[72:73]
	v_addc_co_u32_e64 v131, s[76:77], 0, v131, s[74:75]
	v_cmp_gt_u32_e64 s[68:69], v20, v129
	v_cmp_gt_u32_e64 s[70:71], v21, v129
	v_cmp_gt_u32_e64 s[72:73], v22, v129
	v_cmp_gt_u32_e64 s[74:75], v23, v129
	v_addc_co_u32_e64 v130, s[76:77], 0, v130, s[68:69]
	v_addc_co_u32_e64 v131, s[76:77], 0, v131, s[70:71]
	v_addc_co_u32_e64 v130, s[76:77], 0, v130, s[72:73]
	v_addc_co_u32_e64 v131, s[76:77], 0, v131, s[74:75]
	v_cmp_gt_u32_e64 s[68:69], v24, v129
	v_cmp_gt_u32_e64 s[70:71], v25, v129
	v_cmp_gt_u32_e64 s[72:73], v26, v129
	v_cmp_gt_u32_e64 s[74:75], v27, v129
	v_addc_co_u32_e64 v130, s[76:77], 0, v130, s[68:69]
	v_addc_co_u32_e64 v131, s[76:77], 0, v131, s[70:71]
	v_addc_co_u32_e64 v130, s[76:77], 0, v130, s[72:73]
	v_addc_co_u32_e64 v131, s[76:77], 0, v131, s[74:75]
	v_cmp_gt_u32_e64 s[68:69], v148, v129
	v_cmp_gt_u32_e64 s[70:71], v149, v129
	v_cmp_gt_u32_e64 s[72:73], v150, v129
	v_cmp_gt_u32_e64 s[74:75], v151, v129
	v_addc_co_u32_e64 v130, s[76:77], 0, v130, s[68:69]
	v_addc_co_u32_e64 v131, s[76:77], 0, v131, s[70:71]
	v_addc_co_u32_e64 v130, s[76:77], 0, v130, s[72:73]
	v_addc_co_u32_e64 v131, s[76:77], 0, v131, s[74:75]
	v_add_u32_e32 v130, v130, v131
	v_mov_b32_e32 v131, 0
	v_cmp_gt_u32_e64 s[78:79], 16, v130
	v_add_f32_e32 v132, v124, v125
	v_sub_f32_e32 v132, v128, v132
	s_and_b64 s[78:79], s[78:79], s[4:5]
	v_mul_f32_e32 v132, 0x3fb8aa3b, v132
	v_exp_f32_e32 v132, v132
	v_lshl_add_u32 v136, v126, 7, v127
	v_lshl_add_u64 v[140:141], v[90:91], 0, v[130:131]
	v_cndmask_b32_e64 v132, 0, v132, s[78:79]
	v_lshlrev_b64 v[140:141], 2, v[140:141]
	s_nop 0
	v_add_f32_dpp v133, v132, v132 quad_perm:[1,0,3,2] row_mask:0xf bank_mask:0xf
	v_lshl_add_u64 v[142:143], s[38:39], 0, v[140:141]
	v_lshl_add_u64 v[144:145], s[40:41], 0, v[140:141]
	v_add_f32_dpp v133, v133, v133 quad_perm:[2,3,0,1] row_mask:0xf bank_mask:0xf
	s_nop 1
	v_add_f32_dpp v133, v133, v133 row_half_mirror row_mask:0xf bank_mask:0xf
	s_nop 1
	v_add_f32_dpp v133, v133, v133 row_mirror row_mask:0xf bank_mask:0xf
	s_nop 1
	v_readlane_b32 s80, v133, 0
	v_readlane_b32 s81, v133, 16
	v_readlane_b32 s82, v133, 32
	v_readlane_b32 s83, v133, 48
	v_mov_b32_e32 v134, s80
	s_nop 0
	v_add_f32_e32 v134, s81, v134
	v_add_f32_e32 v134, s82, v134
	v_add_f32_e32 v134, s83, v134
	v_rcp_f32_e32 v134, v134
	s_nop 0
	v_mul_f32_e32 v135, v132, v134
	s_mov_b64 exec, s[78:79]
	global_store_dword v[142:143], v136, off
	global_store_dword v[144:145], v135, off
	s_mov_b64 exec, s[46:47]
	s_addk_i32 s12, 0x410
	v_lshl_add_u64 v[90:91], v[90:91], 0, s[44:45]
	s_cmpk_lg_i32 s12, 0x4100
	s_cbranch_scc1 .Ltk2_loop
